# diff-attention tile loop: K-fragment LDS reads issued directly after the barrier, ahead of the next tile's global loads and the causal early-out test
# speedup vs baseline: 1.0115x; 1.0018x over previous
.LBB0_1747:
	s_bitcmp1_b32 s13, 0
	s_cselect_b32 s0, 0x2400, 0
	s_add_i32 s15, s0, 0
	v_add3_u32 v66, s15, v173, v158
	s_cmp_lt_i32 s12, 1
	s_waitcnt vmcnt(1)
	ds_write_b128 v66, v[146:149]
	s_waitcnt vmcnt(0)
	ds_write_b128 v66, v[150:153] offset:18432
	s_waitcnt lgkmcnt(0)
	s_barrier
	v_add_u32_e32 v66, s15, v186
	v_add_u32_e32 v163, v66, v0
	ds_read_b128 v[82:85], v163
	ds_read_b128 v[86:89], v163 offset:4608
	ds_read_b128 v[90:93], v163 offset:32
	ds_read_b128 v[94:97], v163 offset:4640
	ds_read_b128 v[212:215], v163 offset:64
	ds_read_b128 v[220:223], v163 offset:4672
	ds_read_b128 v[240:243], v163 offset:96
	ds_read_b128 v[244:247], v163 offset:4704
	s_cbranch_scc1 .LBB0_1749
	s_add_i32 s0, s12, -1
	v_mad_u64_u32 v[66:67], s[0:1], s0, v230, v[160:161]
	global_load_dwordx4 v[146:149], v[66:67], off offset:512
	global_load_dwordx4 v[150:153], v[66:67], off offset:1024
.LBB0_1749:
	s_sub_i32 s0, s14, 63
	v_cmp_le_i32_e32 vcc, s0, v174
	s_and_saveexec_b64 s[6:7], vcc
	s_cbranch_execz .LBB0_1746
	s_mov_b32 s69, s68
	s_mov_b32 s70, s68
	s_mov_b32 s71, s68
	s_mov_b32 s72, s68
	s_mov_b32 s73, s68
	s_mov_b32 s74, s68
	s_mov_b32 s75, s68
	s_mov_b32 s76, s68
	s_mov_b32 s77, s68
	s_mov_b32 s78, s68
	s_mov_b32 s79, s68
	s_mov_b32 s80, s68
	s_mov_b32 s81, s68
	s_mov_b32 s82, s68
	s_mov_b32 s83, s68
	v_cmp_gt_i32_e32 vcc, s14, v172
	s_waitcnt lgkmcnt(7)
	v_mfma_f32_32x32x16_bf16 v[114:129], v[82:85], v[130:133], 0
	s_waitcnt lgkmcnt(6)
	v_mfma_f32_32x32x16_bf16 v[98:113], v[86:89], v[130:133], 0
	s_waitcnt lgkmcnt(5)
	v_mfma_f32_32x32x16_bf16 v[114:129], v[90:93], v[134:137], v[114:129]
	s_waitcnt lgkmcnt(4)
	v_mfma_f32_32x32x16_bf16 v[98:113], v[94:97], v[134:137], v[98:113]
	s_and_saveexec_b64 s[8:9], vcc
	s_cbranch_execz .LBB0_1752
	v_add_u32_e32 v70, s14, v157
	v_subrev_u32_e32 v205, 63, v70
	v_subrev_u32_e32 v211, 31, v70
	v_subrev_u32_e32 v210, 30, v70
	v_subrev_u32_e32 v209, 61, v70
	v_subrev_u32_e32 v208, 29, v70
	v_subrev_u32_e32 v207, 60, v70
	v_subrev_u32_e32 v206, 28, v70
	v_subrev_u32_e32 v204, 55, v70
	v_subrev_u32_e32 v203, 23, v70
	v_subrev_u32_e32 v202, 54, v70
	v_subrev_u32_e32 v201, 22, v70
	v_subrev_u32_e32 v200, 53, v70
	v_subrev_u32_e32 v199, 21, v70
	v_subrev_u32_e32 v198, 52, v70
	v_subrev_u32_e32 v197, 20, v70
	v_subrev_u32_e32 v196, 47, v70
	v_add_u32_e32 v195, -15, v70
	v_subrev_u32_e32 v194, 46, v70
	v_add_u32_e32 v193, -14, v70
	v_subrev_u32_e32 v192, 45, v70
	v_add_u32_e32 v191, -13, v70
	v_subrev_u32_e32 v190, 44, v70
	v_add_u32_e32 v171, -12, v70
	v_subrev_u32_e32 v170, 39, v70
	v_add_u32_e32 v169, -7, v70
	v_subrev_u32_e32 v168, 38, v70
	v_add_u32_e32 v167, -6, v70
	v_subrev_u32_e32 v166, 37, v70
	v_add_u32_e32 v165, -5, v70
	v_subrev_u32_e32 v164, 36, v70
	v_add_u32_e32 v162, -4, v70
	v_cmp_le_i32_e64 s[0:1], v211, v156
	s_nop 1
	v_cndmask_b32_e64 v98, v236, v98, s[0:1]
	v_cmp_lt_i32_e64 s[0:1], v205, v156
	s_nop 1
	v_cndmask_b32_e64 v115, v236, v115, s[0:1]
	v_cmp_le_i32_e64 s[0:1], v205, v156
	s_nop 1
	v_cndmask_b32_e64 v114, v236, v114, s[0:1]
	v_cmp_le_i32_e64 s[0:1], v210, v156
	s_nop 1
	v_cndmask_b32_e64 v99, v236, v99, s[0:1]
	v_cmp_le_i32_e64 s[0:1], v209, v156
	s_nop 1
	v_cndmask_b32_e64 v116, v236, v116, s[0:1]
	v_cmp_le_i32_e64 s[0:1], v208, v156
	s_nop 1
	v_cndmask_b32_e64 v100, v236, v100, s[0:1]
	v_cmp_le_i32_e64 s[0:1], v207, v156
	s_nop 1
	v_cndmask_b32_e64 v117, v236, v117, s[0:1]
	v_cmp_le_i32_e64 s[0:1], v206, v156
	s_nop 1
	v_cndmask_b32_e64 v101, v236, v101, s[0:1]
	v_cmp_le_i32_e64 s[0:1], v204, v156
	s_nop 1
	v_cndmask_b32_e64 v118, v236, v118, s[0:1]
	v_cmp_le_i32_e64 s[0:1], v203, v156
	s_nop 1
	v_cndmask_b32_e64 v102, v236, v102, s[0:1]
	v_cmp_le_i32_e64 s[0:1], v202, v156
	s_nop 1
	v_cndmask_b32_e64 v119, v236, v119, s[0:1]
	v_cmp_le_i32_e64 s[0:1], v201, v156
	s_nop 1
	v_cndmask_b32_e64 v103, v236, v103, s[0:1]
	v_cmp_le_i32_e64 s[0:1], v200, v156
	s_nop 1
	v_cndmask_b32_e64 v120, v236, v120, s[0:1]
	v_cmp_le_i32_e64 s[0:1], v199, v156
	s_nop 1
	v_cndmask_b32_e64 v104, v236, v104, s[0:1]
	v_cmp_le_i32_e64 s[0:1], v198, v156
	s_nop 1
	v_cndmask_b32_e64 v121, v236, v121, s[0:1]
	v_cmp_le_i32_e64 s[0:1], v197, v156
	s_nop 1
	v_cndmask_b32_e64 v105, v236, v105, s[0:1]
	v_cmp_le_i32_e64 s[0:1], v196, v156
	s_nop 1
	v_cndmask_b32_e64 v122, v236, v122, s[0:1]
	v_cmp_le_i32_e64 s[0:1], v195, v156
	s_nop 1
	v_cndmask_b32_e64 v106, v236, v106, s[0:1]
	v_cmp_le_i32_e64 s[0:1], v194, v156
	s_nop 1
	v_cndmask_b32_e64 v123, v236, v123, s[0:1]
	v_cmp_le_i32_e64 s[0:1], v193, v156
	s_nop 1
	v_cndmask_b32_e64 v107, v236, v107, s[0:1]
	v_cmp_le_i32_e64 s[0:1], v192, v156
	s_nop 1
	v_cndmask_b32_e64 v124, v236, v124, s[0:1]
	v_cmp_le_i32_e64 s[0:1], v191, v156
	s_nop 1
	v_cndmask_b32_e64 v108, v236, v108, s[0:1]
	v_cmp_le_i32_e64 s[0:1], v190, v156
	s_nop 1
	v_cndmask_b32_e64 v125, v236, v125, s[0:1]
	v_cmp_le_i32_e64 s[0:1], v171, v156
	s_nop 1
	v_cndmask_b32_e64 v109, v236, v109, s[0:1]
	v_cmp_le_i32_e64 s[0:1], v170, v156
	s_nop 1
	v_cndmask_b32_e64 v126, v236, v126, s[0:1]
	v_cmp_le_i32_e64 s[0:1], v169, v156
	s_nop 1
	v_cndmask_b32_e64 v110, v236, v110, s[0:1]
	v_cmp_le_i32_e64 s[0:1], v168, v156
	s_nop 1
	v_cndmask_b32_e64 v127, v236, v127, s[0:1]
	v_cmp_le_i32_e64 s[0:1], v167, v156
	s_nop 1
	v_cndmask_b32_e64 v111, v236, v111, s[0:1]
	v_cmp_le_i32_e64 s[0:1], v166, v156
	s_nop 1
	v_cndmask_b32_e64 v128, v236, v128, s[0:1]
	v_cmp_le_i32_e64 s[0:1], v165, v156
	s_nop 1
	v_cndmask_b32_e64 v112, v236, v112, s[0:1]
	v_cmp_le_i32_e64 s[0:1], v164, v156
	s_nop 1
	v_cndmask_b32_e64 v129, v236, v129, s[0:1]
	v_cmp_le_i32_e64 s[0:1], v162, v156
	s_nop 1
	v_cndmask_b32_e64 v113, v236, v113, s[0:1]
